# NSA top-16 selection: lane-xor argmax exchange via DPP + v_cndmask instead of ds_bpermute pairs and exec-masked branches
# baseline (speedup 1.0000x reference)
.LBB0_1619:
	s_waitcnt lgkmcnt(0)
	ds_read_b128 v[58:61], v9 offset:37376
	ds_read_b128 v[62:65], v9 offset:37392
	ds_read_b128 v[66:69], v9 offset:37408
	ds_read_b128 v[70:73], v9 offset:37424
	s_waitcnt lgkmcnt(3)
	v_cmp_ne_u32_e64 s[0:1], 0, v58
	v_max_u32_e32 v74, v59, v58
	s_nop 0
	v_cndmask_b32_e64 v0, 0, v8, s[0:1]
	v_cmp_gt_u32_e64 s[0:1], v59, v58
	v_max_u32_e32 v58, v60, v74
	v_max_u32_e32 v59, v61, v58
	v_cndmask_b32_e64 v0, v0, v12, s[0:1]
	v_cmp_gt_u32_e64 s[0:1], v60, v74
	s_nop 1
	v_cndmask_b32_e64 v0, v0, v11, s[0:1]
	v_cmp_gt_u32_e64 s[0:1], v61, v58
	s_waitcnt lgkmcnt(2)
	v_max_u32_e32 v58, v62, v59
	v_cndmask_b32_e64 v0, v0, v13, s[0:1]
	v_cmp_gt_u32_e64 s[0:1], v62, v59
	v_max_u32_e32 v59, v63, v58
	s_nop 0
	v_cndmask_b32_e64 v0, v0, v15, s[0:1]
	v_cmp_gt_u32_e64 s[0:1], v63, v58
	v_max_u32_e32 v58, v64, v59
	s_nop 0
	v_cndmask_b32_e64 v0, v0, v14, s[0:1]
	v_cmp_gt_u32_e64 s[0:1], v64, v59
	v_max_u32_e32 v59, v65, v58
	s_nop 0
	v_cndmask_b32_e64 v0, v0, v49, s[0:1]
	v_cmp_gt_u32_e64 s[0:1], v65, v58
	s_waitcnt lgkmcnt(1)
	v_max_u32_e32 v58, v66, v59
	v_cndmask_b32_e64 v0, v0, v48, s[0:1]
	v_cmp_gt_u32_e64 s[0:1], v66, v59
	v_max_u32_e32 v59, v67, v58
	s_nop 0
	v_cndmask_b32_e64 v0, v0, v51, s[0:1]
	v_cmp_gt_u32_e64 s[0:1], v67, v58
	v_max_u32_e32 v58, v68, v59
	s_nop 0
	v_cndmask_b32_e64 v0, v0, v50, s[0:1]
	v_cmp_gt_u32_e64 s[0:1], v68, v59
	v_max_u32_e32 v59, v69, v58
	s_nop 0
	v_cndmask_b32_e64 v0, v0, v53, s[0:1]
	v_cmp_gt_u32_e64 s[0:1], v69, v58
	s_waitcnt lgkmcnt(0)
	v_max_u32_e32 v58, v70, v59
	v_cndmask_b32_e64 v0, v0, v52, s[0:1]
	v_cmp_gt_u32_e64 s[0:1], v70, v59
	v_max_u32_e32 v59, v71, v58
	v_max_u32_e32 v60, v72, v59
	v_cndmask_b32_e64 v0, v0, v55, s[0:1]
	v_cmp_gt_u32_e64 s[0:1], v71, v58
	v_max_u32_e32 v58, v73, v60
	s_nop 0
	v_cndmask_b32_e64 v0, v0, v54, s[0:1]
	v_cmp_gt_u32_e64 s[0:1], v72, v59
	s_nop 1
	v_cndmask_b32_e64 v0, v0, v57, s[0:1]
	v_cmp_gt_u32_e64 s[0:1], v73, v60
	s_nop 1
	v_cndmask_b32_e64 v0, v0, v56, s[0:1]
	s_nop 1
	v_mov_b32_dpp v59, v58 quad_perm:[1,0,3,2] row_mask:0xf bank_mask:0xf
	v_mov_b32_dpp v60, v0 quad_perm:[1,0,3,2] row_mask:0xf bank_mask:0xf
	v_cmp_gt_u32_e64 s[4:5], v59, v58
	v_cmp_eq_u32_e64 s[0:1], v59, v58
	v_cmp_lt_i32_e64 s[2:3], v60, v0
	s_and_b64 s[0:1], s[0:1], s[2:3]
	s_or_b64 s[4:5], s[4:5], s[0:1]
	v_cndmask_b32_e64 v58, v58, v59, s[4:5]
	v_cndmask_b32_e64 v0, v0, v60, s[4:5]
	s_nop 1
	v_mov_b32_dpp v59, v58 quad_perm:[2,3,0,1] row_mask:0xf bank_mask:0xf
	v_mov_b32_dpp v60, v0 quad_perm:[2,3,0,1] row_mask:0xf bank_mask:0xf
	v_cmp_gt_u32_e64 s[4:5], v59, v58
	v_cmp_eq_u32_e64 s[0:1], v59, v58
	v_cmp_lt_i32_e64 s[2:3], v60, v0
	s_and_b64 s[0:1], s[0:1], s[2:3]
	s_or_b64 s[4:5], s[4:5], s[0:1]
	v_cndmask_b32_e64 v58, v58, v59, s[4:5]
	v_cndmask_b32_e64 v0, v0, v60, s[4:5]
	s_nop 1
	v_mov_b32_dpp v59, v58 row_half_mirror row_mask:0xf bank_mask:0xf
	v_mov_b32_dpp v60, v0 row_half_mirror row_mask:0xf bank_mask:0xf
	v_cmp_gt_u32_e64 s[4:5], v59, v58
	v_cmp_eq_u32_e64 s[0:1], v59, v58
	v_cmp_lt_i32_e64 s[2:3], v60, v0
	s_and_b64 s[0:1], s[0:1], s[2:3]
	s_or_b64 s[4:5], s[4:5], s[0:1]
	v_cndmask_b32_e64 v58, v58, v59, s[4:5]
	v_cndmask_b32_e64 v0, v0, v60, s[4:5]
	v_cmp_ne_u32_e64 s[0:1], 0, v58
	s_and_saveexec_b64 s[2:3], s[0:1]
	s_cbranch_execz .LBB0_1618
